# sample-row split-K GEMM (K=2816 instances): all 22 operand pairs of a wave requested up front
# speedup vs baseline: 1.0184x; 1.0050x over previous
; template <int MODE>
; __device__ __forceinline__ void small_gemm(LAS unsigned char* lds, const bf16* A, const bf16* Bt, int N, int K, bf16* O, int ldc, int act_cols, const float* bias, const bf16* Yv, int ldy, int it0, int it1) {
;     ...
;     for (int it = it0; it < it1; ++it) {
;         const int item = BX + it * GSZ; if (item >= nitems) break;
;         const int rt = item & 3, ct = item >> 2;
;         const int hc = 32 * ct + tl;
;         const int brow = (MODE == 3) ? (256 * (hc >> 7) + (hc & 127)) : hc;
;         const bf16* ap = A + (size_t)(32 * rt + tl) * K + wave * kw + 8 * hh;
;         const bf16* bp = Bt + (size_t)brow * K + wave * kw + 8 * hh;
;         v16f acc0, acc1;
; #pragma unroll
;         for (int r = 0; r < 16; ++r) { acc0[r] = 0.f; acc1[r] = 0.f; }
; #pragma unroll 4
;         for (int ks = 0; ks < nks; ++ks) {
;             const bfx8 a = *(const bfx8*)(ap + 16 * ks);
;             const bfx8 b0 = *(const bfx8*)(bp + 16 * ks);
;             acc0 = __builtin_amdgcn_mfma_f32_32x32x16_bf16(b0, a, acc0, 0, 0, 0);
;             if (MODE == 3) { const bfx8 b1 = *(const bfx8*)(bp + (size_t)128 * K + 16 * ks); acc1 = __builtin_amdgcn_mfma_f32_32x32x16_bf16(b1, a, acc1, 0, 0, 0); }
;         }
;         __syncthreads();
; #pragma unroll
;         for (int r = 0; r < 16; ++r) { red[(wave * 16 + r) * 64 + lane] = acc0[r]; if (MODE == 3) red[8192 + (wave * 16 + r) * 64 + lane] = acc1[r]; }
;         __syncthreads();
;         float v0[2], v1[2];
; #pragma unroll
;         for (int e = 0; e < 2; ++e) { float s0 = 0.f, s1 = 0.f;
; #pragma unroll
;             for (int w = 0; w < 8; ++w) { s0 += red[(w * 16 + 2 * wave + e) * 64 + lane]; if (MODE == 3) s1 += red[8192 + (w * 16 + 2 * wave + e) * 64 + lane]; }
;             v0[e] = s0; v1[e] = s1; }
;         const int reg = 2 * wave;
;         const int col = 32 * ct + (reg & 3) + 8 * (reg >> 2) + 4 * hh;
;         const size_t row = (size_t)(32 * rt + tl);
;         float o0 = v0[0], o1 = v0[1];
;         if (MODE == 1) { if (col < act_cols) { o0 = gelu_t(o0); o1 = gelu_t(o1); } }
;         if (MODE == 2) { const unsigned y = *(const unsigned*)(Yv + row * ldy + col); o0 = bf_lo(y) * pg8::sigmoid_f(o0 + bias[col]); o1 = bf_hi(y) * pg8::sigmoid_f(o1 + bias[col + 1]); }
;         if (MODE == 3) { o0 = pg8::silu_f(o0) * v1[0]; o1 = pg8::silu_f(o1) * v1[1]; }
.LBB0_280:
	s_add_i32 s10, s10, s94
	s_cmpk_gt_i32 s10, 0x7f
	s_mov_b64 s[8:9], -1
	s_cbranch_scc1 .LBB0_279
	s_and_b32 s3, s13, 0xffffffe0
	v_or_b32_e32 v0, s3, v22
	v_mad_i64_i32 v[54:55], s[0:1], v0, s11, v[20:21]
	global_load_dwordx4 v[58:61], v[54:55], off
	s_and_b32 s8, s14, 0x60
	v_or_b32_e32 v16, s8, v22
	v_mad_u64_u32 v[56:57], s[0:1], v16, s11, v[18:19]
	s_add_i32 s12, s12, -1
	s_add_i32 s13, s13, s46
	s_add_i32 s14, s14, s71
	v_lshlrev_b32_e32 v16, 11, v16
	s_cmp_eq_u32 s12, 0
	s_cselect_b64 s[8:9], -1, 0
	global_load_dwordx4 v[62:65], v[56:57], off
	global_load_dwordx4 v[66:69], v[54:55], off offset:32
	global_load_dwordx4 v[70:73], v[56:57], off offset:32
	global_load_dwordx4 v[74:77], v[54:55], off offset:64
	global_load_dwordx4 v[78:81], v[56:57], off offset:64
	global_load_dwordx4 v[82:85], v[54:55], off offset:96
	global_load_dwordx4 v[86:89], v[56:57], off offset:96
	global_load_dwordx4 v[90:93], v[54:55], off offset:128
	global_load_dwordx4 v[94:97], v[56:57], off offset:128
	global_load_dwordx4 v[98:101], v[54:55], off offset:160
	global_load_dwordx4 v[102:105], v[56:57], off offset:160
	global_load_dwordx4 v[106:109], v[54:55], off offset:192
	global_load_dwordx4 v[110:113], v[56:57], off offset:192
	global_load_dwordx4 v[114:117], v[54:55], off offset:224
	global_load_dwordx4 v[118:121], v[56:57], off offset:224
	global_load_dwordx4 v[122:125], v[54:55], off offset:256
	global_load_dwordx4 v[126:129], v[56:57], off offset:256
	global_load_dwordx4 v[130:133], v[54:55], off offset:288
	global_load_dwordx4 v[134:137], v[56:57], off offset:288
	global_load_dwordx4 v[138:141], v[54:55], off offset:320
	global_load_dwordx4 v[142:145], v[56:57], off offset:320
	global_load_dwordx4 v[146:149], v[54:55], off offset:352
	global_load_dwordx4 v[150:153], v[56:57], off offset:352
	global_load_dwordx4 v[154:157], v[54:55], off offset:384
	global_load_dwordx4 v[158:161], v[56:57], off offset:384
	global_load_dwordx4 v[162:165], v[54:55], off offset:416
	global_load_dwordx4 v[166:169], v[56:57], off offset:416
	global_load_dwordx4 v[170:173], v[54:55], off offset:448
	global_load_dwordx4 v[174:177], v[56:57], off offset:448
	global_load_dwordx4 v[178:181], v[54:55], off offset:480
	global_load_dwordx4 v[192:195], v[56:57], off offset:480
	global_load_dwordx4 v[196:199], v[54:55], off offset:512
	global_load_dwordx4 v[200:203], v[56:57], off offset:512
	global_load_dwordx4 v[204:207], v[54:55], off offset:544
	global_load_dwordx4 v[208:211], v[56:57], off offset:544
	global_load_dwordx4 v[212:215], v[54:55], off offset:576
	global_load_dwordx4 v[216:219], v[56:57], off offset:576
	global_load_dwordx4 v[220:223], v[54:55], off offset:608
	global_load_dwordx4 v[224:227], v[56:57], off offset:608
	global_load_dwordx4 v[228:231], v[54:55], off offset:640
	global_load_dwordx4 v[234:237], v[56:57], off offset:640
	global_load_dwordx4 v[238:241], v[54:55], off offset:672
	global_load_dwordx4 v[242:245], v[56:57], off offset:672
	s_waitcnt vmcnt(42)
	v_mfma_f32_32x32x16_bf16 v[0:15], v[58:61], v[62:65], 0
	s_waitcnt vmcnt(40)
	v_mfma_f32_32x32x16_bf16 v[0:15], v[66:69], v[70:73], v[0:15]
	s_waitcnt vmcnt(38)
	v_mfma_f32_32x32x16_bf16 v[0:15], v[74:77], v[78:81], v[0:15]
	s_waitcnt vmcnt(36)
	v_mfma_f32_32x32x16_bf16 v[0:15], v[82:85], v[86:89], v[0:15]
	s_waitcnt vmcnt(34)
	v_mfma_f32_32x32x16_bf16 v[0:15], v[90:93], v[94:97], v[0:15]
	s_waitcnt vmcnt(32)
	v_mfma_f32_32x32x16_bf16 v[0:15], v[98:101], v[102:105], v[0:15]
	s_waitcnt vmcnt(30)
	v_mfma_f32_32x32x16_bf16 v[0:15], v[106:109], v[110:113], v[0:15]
	s_waitcnt vmcnt(28)
	v_mfma_f32_32x32x16_bf16 v[0:15], v[114:117], v[118:121], v[0:15]
	s_waitcnt vmcnt(26)
	v_mfma_f32_32x32x16_bf16 v[0:15], v[122:125], v[126:129], v[0:15]
	s_waitcnt vmcnt(24)
	v_mfma_f32_32x32x16_bf16 v[0:15], v[130:133], v[134:137], v[0:15]
	s_waitcnt vmcnt(22)
	v_mfma_f32_32x32x16_bf16 v[0:15], v[138:141], v[142:145], v[0:15]
	s_waitcnt vmcnt(20)
	v_mfma_f32_32x32x16_bf16 v[0:15], v[146:149], v[150:153], v[0:15]
	s_waitcnt vmcnt(18)
	v_mfma_f32_32x32x16_bf16 v[0:15], v[154:157], v[158:161], v[0:15]
	s_waitcnt vmcnt(16)
	v_mfma_f32_32x32x16_bf16 v[0:15], v[162:165], v[166:169], v[0:15]
	s_waitcnt vmcnt(14)
	v_mfma_f32_32x32x16_bf16 v[0:15], v[170:173], v[174:177], v[0:15]
	s_waitcnt vmcnt(12)
	v_mfma_f32_32x32x16_bf16 v[0:15], v[178:181], v[192:195], v[0:15]
	s_waitcnt vmcnt(10)
	v_mfma_f32_32x32x16_bf16 v[0:15], v[196:199], v[200:203], v[0:15]
	s_waitcnt vmcnt(8)
	v_mfma_f32_32x32x16_bf16 v[0:15], v[204:207], v[208:211], v[0:15]
	s_waitcnt vmcnt(6)
	v_mfma_f32_32x32x16_bf16 v[0:15], v[212:215], v[216:219], v[0:15]
	s_waitcnt vmcnt(4)
	v_mfma_f32_32x32x16_bf16 v[0:15], v[220:223], v[224:227], v[0:15]
	s_waitcnt vmcnt(2)
	v_mfma_f32_32x32x16_bf16 v[0:15], v[228:231], v[234:237], v[0:15]
	s_waitcnt vmcnt(0)
	v_mfma_f32_32x32x16_bf16 v[0:15], v[238:241], v[242:245], v[0:15]
	s_barrier
	v_add_u32_e32 v26, s3, v23
	v_ashrrev_i32_e32 v27, 31, v26
	v_lshl_add_u64 v[28:29], s[6:7], 0, v[16:17]
	v_lshl_add_u64 v[26:27], v[26:27], 1, v[28:29]
	s_nop 11
	ds_write2st64_b32 v24, v0, v1 offset1:1
	ds_write2st64_b32 v24, v2, v3 offset0:2 offset1:3
	ds_write2st64_b32 v24, v4, v5 offset0:4 offset1:5
	ds_write2st64_b32 v24, v6, v7 offset0:6 offset1:7
	ds_write2st64_b32 v24, v8, v9 offset0:8 offset1:9
	ds_write2st64_b32 v24, v10, v11 offset0:10 offset1:11
	ds_write2st64_b32 v24, v12, v13 offset0:12 offset1:13
	ds_write2st64_b32 v24, v14, v15 offset0:14 offset1:15
	s_waitcnt lgkmcnt(0)
	s_barrier
	ds_read2st64_b32 v[0:1], v25 offset1:1
	ds_read2st64_b32 v[2:3], v25 offset0:16 offset1:17
	ds_read2st64_b32 v[4:5], v25 offset0:32 offset1:33
	ds_read2st64_b32 v[6:7], v25 offset0:48 offset1:49
	ds_read2st64_b32 v[8:9], v25 offset0:64 offset1:65
	ds_read2st64_b32 v[10:11], v25 offset0:80 offset1:81
	ds_read2st64_b32 v[12:13], v25 offset0:96 offset1:97
	ds_read2st64_b32 v[14:15], v25 offset0:112 offset1:113
	s_waitcnt lgkmcnt(7)
	v_add_f32_e32 v0, 0, v0
	v_add_f32_e32 v1, 0, v1
	s_waitcnt lgkmcnt(6)
	v_add_f32_e32 v0, v0, v2
	v_add_f32_e32 v1, v1, v3
	s_waitcnt lgkmcnt(5)
	v_add_f32_e32 v0, v0, v4
	v_add_f32_e32 v1, v1, v5
	s_waitcnt lgkmcnt(4)
	v_add_f32_e32 v0, v0, v6
	v_add_f32_e32 v1, v1, v7
	s_waitcnt lgkmcnt(3)
	v_add_f32_e32 v0, v0, v8
	v_add_f32_e32 v1, v1, v9
	s_waitcnt lgkmcnt(2)
	v_add_f32_e32 v0, v0, v10
	v_add_f32_e32 v1, v1, v11
	s_waitcnt lgkmcnt(1)
	v_add_f32_e32 v0, v0, v12
	v_add_f32_e32 v1, v1, v13
	s_waitcnt lgkmcnt(0)
	v_add_f32_e32 v0, v0, v14
	v_add_f32_e32 v1, v1, v15
	v_cvt_pk_bf16_f32 v0, v0, v1
	global_store_dword v[26:27], v0, off
	s_branch .LBB0_279

; template <int MODE>
; __device__ __forceinline__ void small_gemm(LAS unsigned char* lds, const bf16* A, const bf16* Bt, int N, int K, bf16* O, int ldc, int act_cols, const float* bias, const bf16* Yv, int ldy, int it0, int it1) {
;     ...
;     for (int it = it0; it < it1; ++it) {
;         const int item = BX + it * GSZ; if (item >= nitems) break;
;         const int rt = item & 3, ct = item >> 2;
;         const int hc = 32 * ct + tl;
;         const int brow = (MODE == 3) ? (256 * (hc >> 7) + (hc & 127)) : hc;
;         const bf16* ap = A + (size_t)(32 * rt + tl) * K + wave * kw + 8 * hh;
;         const bf16* bp = Bt + (size_t)brow * K + wave * kw + 8 * hh;
;         v16f acc0, acc1;
; #pragma unroll
;         for (int r = 0; r < 16; ++r) { acc0[r] = 0.f; acc1[r] = 0.f; }
; #pragma unroll 4
;         for (int ks = 0; ks < nks; ++ks) {
;             const bfx8 a = *(const bfx8*)(ap + 16 * ks);
;             const bfx8 b0 = *(const bfx8*)(bp + 16 * ks);
;             acc0 = __builtin_amdgcn_mfma_f32_32x32x16_bf16(b0, a, acc0, 0, 0, 0);
;             if (MODE == 3) { const bfx8 b1 = *(const bfx8*)(bp + (size_t)128 * K + 16 * ks); acc1 = __builtin_amdgcn_mfma_f32_32x32x16_bf16(b1, a, acc1, 0, 0, 0); }
;         }
;         __syncthreads();
; #pragma unroll
;         for (int r = 0; r < 16; ++r) { red[(wave * 16 + r) * 64 + lane] = acc0[r]; if (MODE == 3) red[8192 + (wave * 16 + r) * 64 + lane] = acc1[r]; }
;         __syncthreads();
;         float v0[2], v1[2];
; #pragma unroll
;         for (int e = 0; e < 2; ++e) { float s0 = 0.f, s1 = 0.f;
; #pragma unroll
;             for (int w = 0; w < 8; ++w) { s0 += red[(w * 16 + 2 * wave + e) * 64 + lane]; if (MODE == 3) s1 += red[8192 + (w * 16 + 2 * wave + e) * 64 + lane]; }
;             v0[e] = s0; v1[e] = s1; }
;         const int reg = 2 * wave;
;         const int col = 32 * ct + (reg & 3) + 8 * (reg >> 2) + 4 * hh;
;         const size_t row = (size_t)(32 * rt + tl);
;         float o0 = v0[0], o1 = v0[1];
;         if (MODE == 1) { if (col < act_cols) { o0 = gelu_t(o0); o1 = gelu_t(o1); } }
;         if (MODE == 2) { const unsigned y = *(const unsigned*)(Yv + row * ldy + col); o0 = bf_lo(y) * pg8::sigmoid_f(o0 + bias[col]); o1 = bf_hi(y) * pg8::sigmoid_f(o1 + bias[col + 1]); }
;         if (MODE == 3) { o0 = pg8::silu_f(o0) * v1[0]; o1 = pg8::silu_f(o1) * v1[1]; }
.LBB0_312:
	s_add_i32 s11, s11, s94
	s_cmpk_gt_i32 s11, 0x7f
	s_mov_b64 s[8:9], -1
	s_cbranch_scc1 .LBB0_311
	s_and_b32 s3, s13, 0xffffffe0
	v_or_b32_e32 v0, s3, v22
	v_mad_i64_i32 v[54:55], s[0:1], v0, s10, v[20:21]
	global_load_dwordx4 v[58:61], v[54:55], off
	s_and_b32 s8, s14, 0x60
	v_or_b32_e32 v16, s8, v22
	v_mad_u64_u32 v[56:57], s[0:1], v16, s10, v[18:19]
	s_add_i32 s12, s12, 1
	s_add_i32 s13, s13, s46
	s_add_i32 s14, s14, s71
	v_lshlrev_b32_e32 v16, 11, v16
	s_cmp_gt_u32 s12, 2
	s_cselect_b64 s[8:9], -1, 0
	global_load_dwordx4 v[62:65], v[56:57], off
	global_load_dwordx4 v[66:69], v[54:55], off offset:32
	global_load_dwordx4 v[70:73], v[56:57], off offset:32
	global_load_dwordx4 v[74:77], v[54:55], off offset:64
	global_load_dwordx4 v[78:81], v[56:57], off offset:64
	global_load_dwordx4 v[82:85], v[54:55], off offset:96
	global_load_dwordx4 v[86:89], v[56:57], off offset:96
	global_load_dwordx4 v[90:93], v[54:55], off offset:128
	global_load_dwordx4 v[94:97], v[56:57], off offset:128
	global_load_dwordx4 v[98:101], v[54:55], off offset:160
	global_load_dwordx4 v[102:105], v[56:57], off offset:160
	global_load_dwordx4 v[106:109], v[54:55], off offset:192
	global_load_dwordx4 v[110:113], v[56:57], off offset:192
	global_load_dwordx4 v[114:117], v[54:55], off offset:224
	global_load_dwordx4 v[118:121], v[56:57], off offset:224
	global_load_dwordx4 v[122:125], v[54:55], off offset:256
	global_load_dwordx4 v[126:129], v[56:57], off offset:256
	global_load_dwordx4 v[130:133], v[54:55], off offset:288
	global_load_dwordx4 v[134:137], v[56:57], off offset:288
	global_load_dwordx4 v[138:141], v[54:55], off offset:320
	global_load_dwordx4 v[142:145], v[56:57], off offset:320
	global_load_dwordx4 v[146:149], v[54:55], off offset:352
	global_load_dwordx4 v[150:153], v[56:57], off offset:352
	global_load_dwordx4 v[154:157], v[54:55], off offset:384
	global_load_dwordx4 v[158:161], v[56:57], off offset:384
	global_load_dwordx4 v[162:165], v[54:55], off offset:416
	global_load_dwordx4 v[166:169], v[56:57], off offset:416
	global_load_dwordx4 v[170:173], v[54:55], off offset:448
	global_load_dwordx4 v[174:177], v[56:57], off offset:448
	global_load_dwordx4 v[178:181], v[54:55], off offset:480
	global_load_dwordx4 v[192:195], v[56:57], off offset:480
	global_load_dwordx4 v[196:199], v[54:55], off offset:512
	global_load_dwordx4 v[200:203], v[56:57], off offset:512
	global_load_dwordx4 v[204:207], v[54:55], off offset:544
	global_load_dwordx4 v[208:211], v[56:57], off offset:544
	global_load_dwordx4 v[212:215], v[54:55], off offset:576
	global_load_dwordx4 v[216:219], v[56:57], off offset:576
	global_load_dwordx4 v[220:223], v[54:55], off offset:608
	global_load_dwordx4 v[224:227], v[56:57], off offset:608
	global_load_dwordx4 v[228:231], v[54:55], off offset:640
	global_load_dwordx4 v[234:237], v[56:57], off offset:640
	global_load_dwordx4 v[238:241], v[54:55], off offset:672
	global_load_dwordx4 v[242:245], v[56:57], off offset:672
	s_waitcnt vmcnt(42)
	v_mfma_f32_32x32x16_bf16 v[0:15], v[58:61], v[62:65], 0
	s_waitcnt vmcnt(40)
	v_mfma_f32_32x32x16_bf16 v[0:15], v[66:69], v[70:73], v[0:15]
	s_waitcnt vmcnt(38)
	v_mfma_f32_32x32x16_bf16 v[0:15], v[74:77], v[78:81], v[0:15]
	s_waitcnt vmcnt(36)
	v_mfma_f32_32x32x16_bf16 v[0:15], v[82:85], v[86:89], v[0:15]
	s_waitcnt vmcnt(34)
	v_mfma_f32_32x32x16_bf16 v[0:15], v[90:93], v[94:97], v[0:15]
	s_waitcnt vmcnt(32)
	v_mfma_f32_32x32x16_bf16 v[0:15], v[98:101], v[102:105], v[0:15]
	s_waitcnt vmcnt(30)
	v_mfma_f32_32x32x16_bf16 v[0:15], v[106:109], v[110:113], v[0:15]
	s_waitcnt vmcnt(28)
	v_mfma_f32_32x32x16_bf16 v[0:15], v[114:117], v[118:121], v[0:15]
	s_waitcnt vmcnt(26)
	v_mfma_f32_32x32x16_bf16 v[0:15], v[122:125], v[126:129], v[0:15]
	s_waitcnt vmcnt(24)
	v_mfma_f32_32x32x16_bf16 v[0:15], v[130:133], v[134:137], v[0:15]
	s_waitcnt vmcnt(22)
	v_mfma_f32_32x32x16_bf16 v[0:15], v[138:141], v[142:145], v[0:15]
	s_waitcnt vmcnt(20)
	v_mfma_f32_32x32x16_bf16 v[0:15], v[146:149], v[150:153], v[0:15]
	s_waitcnt vmcnt(18)
	v_mfma_f32_32x32x16_bf16 v[0:15], v[154:157], v[158:161], v[0:15]
	s_waitcnt vmcnt(16)
	v_mfma_f32_32x32x16_bf16 v[0:15], v[162:165], v[166:169], v[0:15]
	s_waitcnt vmcnt(14)
	v_mfma_f32_32x32x16_bf16 v[0:15], v[170:173], v[174:177], v[0:15]
	s_waitcnt vmcnt(12)
	v_mfma_f32_32x32x16_bf16 v[0:15], v[178:181], v[192:195], v[0:15]
	s_waitcnt vmcnt(10)
	v_mfma_f32_32x32x16_bf16 v[0:15], v[196:199], v[200:203], v[0:15]
	s_waitcnt vmcnt(8)
	v_mfma_f32_32x32x16_bf16 v[0:15], v[204:207], v[208:211], v[0:15]
	s_waitcnt vmcnt(6)
	v_mfma_f32_32x32x16_bf16 v[0:15], v[212:215], v[216:219], v[0:15]
	s_waitcnt vmcnt(4)
	v_mfma_f32_32x32x16_bf16 v[0:15], v[220:223], v[224:227], v[0:15]
	s_waitcnt vmcnt(2)
	v_mfma_f32_32x32x16_bf16 v[0:15], v[228:231], v[234:237], v[0:15]
	s_waitcnt vmcnt(0)
	v_mfma_f32_32x32x16_bf16 v[0:15], v[238:241], v[242:245], v[0:15]
	s_barrier
	v_add_u32_e32 v26, s3, v23
	v_ashrrev_i32_e32 v27, 31, v26
	v_lshl_add_u64 v[28:29], s[6:7], 0, v[16:17]
	v_lshl_add_u64 v[26:27], v[26:27], 1, v[28:29]
	s_nop 11
	ds_write2st64_b32 v24, v0, v1 offset1:1
	ds_write2st64_b32 v24, v2, v3 offset0:2 offset1:3
	ds_write2st64_b32 v24, v4, v5 offset0:4 offset1:5
	ds_write2st64_b32 v24, v6, v7 offset0:6 offset1:7
	ds_write2st64_b32 v24, v8, v9 offset0:8 offset1:9
	ds_write2st64_b32 v24, v10, v11 offset0:10 offset1:11
	ds_write2st64_b32 v24, v12, v13 offset0:12 offset1:13
	ds_write2st64_b32 v24, v14, v15 offset0:14 offset1:15
	s_waitcnt lgkmcnt(0)
	s_barrier
	ds_read2st64_b32 v[0:1], v25 offset1:1
	ds_read2st64_b32 v[2:3], v25 offset0:16 offset1:17
	ds_read2st64_b32 v[4:5], v25 offset0:32 offset1:33
	ds_read2st64_b32 v[6:7], v25 offset0:48 offset1:49
	ds_read2st64_b32 v[8:9], v25 offset0:64 offset1:65
	ds_read2st64_b32 v[10:11], v25 offset0:80 offset1:81
	ds_read2st64_b32 v[12:13], v25 offset0:96 offset1:97
	ds_read2st64_b32 v[14:15], v25 offset0:112 offset1:113
	s_waitcnt lgkmcnt(7)
	v_add_f32_e32 v0, 0, v0
	v_add_f32_e32 v1, 0, v1
	s_waitcnt lgkmcnt(6)
	v_add_f32_e32 v0, v0, v2
	v_add_f32_e32 v1, v1, v3
	s_waitcnt lgkmcnt(5)
	v_add_f32_e32 v0, v0, v4
	v_add_f32_e32 v1, v1, v5
	s_waitcnt lgkmcnt(4)
	v_add_f32_e32 v0, v0, v6
	v_add_f32_e32 v1, v1, v7
	s_waitcnt lgkmcnt(3)
	v_add_f32_e32 v0, v0, v8
	v_add_f32_e32 v1, v1, v9
	s_waitcnt lgkmcnt(2)
	v_add_f32_e32 v0, v0, v10
	v_add_f32_e32 v1, v1, v11
	s_waitcnt lgkmcnt(1)
	v_add_f32_e32 v0, v0, v12
	v_add_f32_e32 v1, v1, v13
	s_waitcnt lgkmcnt(0)
	v_add_f32_e32 v0, v0, v14
	v_add_f32_e32 v1, v1, v15
	v_cvt_pk_bf16_f32 v0, v0, v1
	global_store_dword v[26:27], v0, off
	s_branch .LBB0_311

; template <int MODE>
; __device__ __forceinline__ void small_gemm(LAS unsigned char* lds, const bf16* A, const bf16* Bt, int N, int K, bf16* O, int ldc, int act_cols, const float* bias, const bf16* Yv, int ldy, int it0, int it1) {
;     ...
;     for (int it = it0; it < it1; ++it) {
;         const int item = BX + it * GSZ; if (item >= nitems) break;
;         const int rt = item & 3, ct = item >> 2;
;         const int hc = 32 * ct + tl;
;         const int brow = (MODE == 3) ? (256 * (hc >> 7) + (hc & 127)) : hc;
;         const bf16* ap = A + (size_t)(32 * rt + tl) * K + wave * kw + 8 * hh;
;         const bf16* bp = Bt + (size_t)brow * K + wave * kw + 8 * hh;
;         v16f acc0, acc1;
; #pragma unroll
;         for (int r = 0; r < 16; ++r) { acc0[r] = 0.f; acc1[r] = 0.f; }
; #pragma unroll 4
;         for (int ks = 0; ks < nks; ++ks) {
;             const bfx8 a = *(const bfx8*)(ap + 16 * ks);
;             const bfx8 b0 = *(const bfx8*)(bp + 16 * ks);
;             acc0 = __builtin_amdgcn_mfma_f32_32x32x16_bf16(b0, a, acc0, 0, 0, 0);
;             if (MODE == 3) { const bfx8 b1 = *(const bfx8*)(bp + (size_t)128 * K + 16 * ks); acc1 = __builtin_amdgcn_mfma_f32_32x32x16_bf16(b1, a, acc1, 0, 0, 0); }
;         }
;         __syncthreads();
; #pragma unroll
;         for (int r = 0; r < 16; ++r) { red[(wave * 16 + r) * 64 + lane] = acc0[r]; if (MODE == 3) red[8192 + (wave * 16 + r) * 64 + lane] = acc1[r]; }
;         __syncthreads();
;         float v0[2], v1[2];
; #pragma unroll
;         for (int e = 0; e < 2; ++e) { float s0 = 0.f, s1 = 0.f;
; #pragma unroll
;             for (int w = 0; w < 8; ++w) { s0 += red[(w * 16 + 2 * wave + e) * 64 + lane]; if (MODE == 3) s1 += red[8192 + (w * 16 + 2 * wave + e) * 64 + lane]; }
;             v0[e] = s0; v1[e] = s1; }
;         const int reg = 2 * wave;
;         const int col = 32 * ct + (reg & 3) + 8 * (reg >> 2) + 4 * hh;
;         const size_t row = (size_t)(32 * rt + tl);
;         float o0 = v0[0], o1 = v0[1];
;         if (MODE == 1) { if (col < act_cols) { o0 = gelu_t(o0); o1 = gelu_t(o1); } }
;         if (MODE == 2) { const unsigned y = *(const unsigned*)(Yv + row * ldy + col); o0 = bf_lo(y) * pg8::sigmoid_f(o0 + bias[col]); o1 = bf_hi(y) * pg8::sigmoid_f(o1 + bias[col + 1]); }
;         if (MODE == 3) { o0 = pg8::silu_f(o0) * v1[0]; o1 = pg8::silu_f(o1) * v1[1]; }
.LBB0_1186:
	s_add_i32 s12, s12, s94
	s_cmpk_gt_i32 s12, 0x7f
	s_mov_b64 s[10:11], -1
	s_cbranch_scc1 .LBB0_1185
	s_and_b32 s3, s14, 0xffffffe0
	v_or_b32_e32 v0, s3, v22
	v_mad_i64_i32 v[54:55], s[0:1], v0, s13, v[20:21]
	global_load_dwordx4 v[58:61], v[54:55], off
	s_and_b32 s10, s15, 0x60
	v_or_b32_e32 v16, s10, v22
	v_mad_u64_u32 v[56:57], s[0:1], v16, s13, v[18:19]
	s_add_i32 s44, s44, -1
	s_add_i32 s14, s14, s46
	s_add_i32 s15, s15, s71
	v_lshlrev_b32_e32 v16, 11, v16
	s_cmp_eq_u32 s44, 0
	s_cselect_b64 s[10:11], -1, 0
	global_load_dwordx4 v[62:65], v[56:57], off
	global_load_dwordx4 v[66:69], v[54:55], off offset:32
	global_load_dwordx4 v[70:73], v[56:57], off offset:32
	global_load_dwordx4 v[74:77], v[54:55], off offset:64
	global_load_dwordx4 v[78:81], v[56:57], off offset:64
	global_load_dwordx4 v[82:85], v[54:55], off offset:96
	global_load_dwordx4 v[86:89], v[56:57], off offset:96
	global_load_dwordx4 v[90:93], v[54:55], off offset:128
	global_load_dwordx4 v[94:97], v[56:57], off offset:128
	global_load_dwordx4 v[98:101], v[54:55], off offset:160
	global_load_dwordx4 v[102:105], v[56:57], off offset:160
	global_load_dwordx4 v[106:109], v[54:55], off offset:192
	global_load_dwordx4 v[110:113], v[56:57], off offset:192
	global_load_dwordx4 v[114:117], v[54:55], off offset:224
	global_load_dwordx4 v[118:121], v[56:57], off offset:224
	global_load_dwordx4 v[122:125], v[54:55], off offset:256
	global_load_dwordx4 v[126:129], v[56:57], off offset:256
	global_load_dwordx4 v[130:133], v[54:55], off offset:288
	global_load_dwordx4 v[134:137], v[56:57], off offset:288
	global_load_dwordx4 v[138:141], v[54:55], off offset:320
	global_load_dwordx4 v[142:145], v[56:57], off offset:320
	global_load_dwordx4 v[146:149], v[54:55], off offset:352
	global_load_dwordx4 v[150:153], v[56:57], off offset:352
	global_load_dwordx4 v[154:157], v[54:55], off offset:384
	global_load_dwordx4 v[158:161], v[56:57], off offset:384
	global_load_dwordx4 v[162:165], v[54:55], off offset:416
	global_load_dwordx4 v[166:169], v[56:57], off offset:416
	global_load_dwordx4 v[170:173], v[54:55], off offset:448
	global_load_dwordx4 v[174:177], v[56:57], off offset:448
	global_load_dwordx4 v[178:181], v[54:55], off offset:480
	global_load_dwordx4 v[192:195], v[56:57], off offset:480
	global_load_dwordx4 v[196:199], v[54:55], off offset:512
	global_load_dwordx4 v[200:203], v[56:57], off offset:512
	global_load_dwordx4 v[204:207], v[54:55], off offset:544
	global_load_dwordx4 v[208:211], v[56:57], off offset:544
	global_load_dwordx4 v[212:215], v[54:55], off offset:576
	global_load_dwordx4 v[216:219], v[56:57], off offset:576
	global_load_dwordx4 v[220:223], v[54:55], off offset:608
	global_load_dwordx4 v[224:227], v[56:57], off offset:608
	global_load_dwordx4 v[228:231], v[54:55], off offset:640
	global_load_dwordx4 v[234:237], v[56:57], off offset:640
	global_load_dwordx4 v[238:241], v[54:55], off offset:672
	global_load_dwordx4 v[242:245], v[56:57], off offset:672
	s_waitcnt vmcnt(42)
	v_mfma_f32_32x32x16_bf16 v[0:15], v[58:61], v[62:65], 0
	s_waitcnt vmcnt(40)
	v_mfma_f32_32x32x16_bf16 v[0:15], v[66:69], v[70:73], v[0:15]
	s_waitcnt vmcnt(38)
	v_mfma_f32_32x32x16_bf16 v[0:15], v[74:77], v[78:81], v[0:15]
	s_waitcnt vmcnt(36)
	v_mfma_f32_32x32x16_bf16 v[0:15], v[82:85], v[86:89], v[0:15]
	s_waitcnt vmcnt(34)
	v_mfma_f32_32x32x16_bf16 v[0:15], v[90:93], v[94:97], v[0:15]
	s_waitcnt vmcnt(32)
	v_mfma_f32_32x32x16_bf16 v[0:15], v[98:101], v[102:105], v[0:15]
	s_waitcnt vmcnt(30)
	v_mfma_f32_32x32x16_bf16 v[0:15], v[106:109], v[110:113], v[0:15]
	s_waitcnt vmcnt(28)
	v_mfma_f32_32x32x16_bf16 v[0:15], v[114:117], v[118:121], v[0:15]
	s_waitcnt vmcnt(26)
	v_mfma_f32_32x32x16_bf16 v[0:15], v[122:125], v[126:129], v[0:15]
	s_waitcnt vmcnt(24)
	v_mfma_f32_32x32x16_bf16 v[0:15], v[130:133], v[134:137], v[0:15]
	s_waitcnt vmcnt(22)
	v_mfma_f32_32x32x16_bf16 v[0:15], v[138:141], v[142:145], v[0:15]
	s_waitcnt vmcnt(20)
	v_mfma_f32_32x32x16_bf16 v[0:15], v[146:149], v[150:153], v[0:15]
	s_waitcnt vmcnt(18)
	v_mfma_f32_32x32x16_bf16 v[0:15], v[154:157], v[158:161], v[0:15]
	s_waitcnt vmcnt(16)
	v_mfma_f32_32x32x16_bf16 v[0:15], v[162:165], v[166:169], v[0:15]
	s_waitcnt vmcnt(14)
	v_mfma_f32_32x32x16_bf16 v[0:15], v[170:173], v[174:177], v[0:15]
	s_waitcnt vmcnt(12)
	v_mfma_f32_32x32x16_bf16 v[0:15], v[178:181], v[192:195], v[0:15]
	s_waitcnt vmcnt(10)
	v_mfma_f32_32x32x16_bf16 v[0:15], v[196:199], v[200:203], v[0:15]
	s_waitcnt vmcnt(8)
	v_mfma_f32_32x32x16_bf16 v[0:15], v[204:207], v[208:211], v[0:15]
	s_waitcnt vmcnt(6)
	v_mfma_f32_32x32x16_bf16 v[0:15], v[212:215], v[216:219], v[0:15]
	s_waitcnt vmcnt(4)
	v_mfma_f32_32x32x16_bf16 v[0:15], v[220:223], v[224:227], v[0:15]
	s_waitcnt vmcnt(2)
	v_mfma_f32_32x32x16_bf16 v[0:15], v[228:231], v[234:237], v[0:15]
	s_waitcnt vmcnt(0)
	v_mfma_f32_32x32x16_bf16 v[0:15], v[238:241], v[242:245], v[0:15]
	s_barrier
	v_add_u32_e32 v26, s3, v23
	v_ashrrev_i32_e32 v27, 31, v26
	v_lshl_add_u64 v[28:29], s[4:5], 0, v[16:17]
	v_lshl_add_u64 v[26:27], v[26:27], 1, v[28:29]
	s_nop 11
	ds_write2st64_b32 v24, v0, v1 offset1:1
	ds_write2st64_b32 v24, v2, v3 offset0:2 offset1:3
	ds_write2st64_b32 v24, v4, v5 offset0:4 offset1:5
	ds_write2st64_b32 v24, v6, v7 offset0:6 offset1:7
	ds_write2st64_b32 v24, v8, v9 offset0:8 offset1:9
	ds_write2st64_b32 v24, v10, v11 offset0:10 offset1:11
	ds_write2st64_b32 v24, v12, v13 offset0:12 offset1:13
	ds_write2st64_b32 v24, v14, v15 offset0:14 offset1:15
	s_waitcnt lgkmcnt(0)
	s_barrier
	ds_read2st64_b32 v[0:1], v25 offset1:1
	ds_read2st64_b32 v[2:3], v25 offset0:16 offset1:17
	ds_read2st64_b32 v[4:5], v25 offset0:32 offset1:33
	ds_read2st64_b32 v[6:7], v25 offset0:48 offset1:49
	ds_read2st64_b32 v[8:9], v25 offset0:64 offset1:65
	ds_read2st64_b32 v[10:11], v25 offset0:80 offset1:81
	ds_read2st64_b32 v[12:13], v25 offset0:96 offset1:97
	ds_read2st64_b32 v[14:15], v25 offset0:112 offset1:113
	s_waitcnt lgkmcnt(7)
	v_add_f32_e32 v0, 0, v0
	v_add_f32_e32 v1, 0, v1
	s_waitcnt lgkmcnt(6)
	v_add_f32_e32 v0, v0, v2
	v_add_f32_e32 v1, v1, v3
	s_waitcnt lgkmcnt(5)
	v_add_f32_e32 v0, v0, v4
	v_add_f32_e32 v1, v1, v5
	s_waitcnt lgkmcnt(4)
	v_add_f32_e32 v0, v0, v6
	v_add_f32_e32 v1, v1, v7
	s_waitcnt lgkmcnt(3)
	v_add_f32_e32 v0, v0, v8
	v_add_f32_e32 v1, v1, v9
	s_waitcnt lgkmcnt(2)
	v_add_f32_e32 v0, v0, v10
	v_add_f32_e32 v1, v1, v11
	s_waitcnt lgkmcnt(1)
	v_add_f32_e32 v0, v0, v12
	v_add_f32_e32 v1, v1, v13
	s_waitcnt lgkmcnt(0)
	v_add_f32_e32 v0, v0, v14
	v_add_f32_e32 v1, v1, v15
	v_cvt_pk_bf16_f32 v0, v0, v1
	global_store_dword v[26:27], v0, off
	s_branch .LBB0_1185

; template <int MODE>
; __device__ __forceinline__ void small_gemm(LAS unsigned char* lds, const bf16* A, const bf16* Bt, int N, int K, bf16* O, int ldc, int act_cols, const float* bias, const bf16* Yv, int ldy, int it0, int it1) {
;     ...
;     for (int it = it0; it < it1; ++it) {
;         const int item = BX + it * GSZ; if (item >= nitems) break;
;         const int rt = item & 3, ct = item >> 2;
;         const int hc = 32 * ct + tl;
;         const int brow = (MODE == 3) ? (256 * (hc >> 7) + (hc & 127)) : hc;
;         const bf16* ap = A + (size_t)(32 * rt + tl) * K + wave * kw + 8 * hh;
;         const bf16* bp = Bt + (size_t)brow * K + wave * kw + 8 * hh;
;         v16f acc0, acc1;
; #pragma unroll
;         for (int r = 0; r < 16; ++r) { acc0[r] = 0.f; acc1[r] = 0.f; }
; #pragma unroll 4
;         for (int ks = 0; ks < nks; ++ks) {
;             const bfx8 a = *(const bfx8*)(ap + 16 * ks);
;             const bfx8 b0 = *(const bfx8*)(bp + 16 * ks);
;             acc0 = __builtin_amdgcn_mfma_f32_32x32x16_bf16(b0, a, acc0, 0, 0, 0);
;             if (MODE == 3) { const bfx8 b1 = *(const bfx8*)(bp + (size_t)128 * K + 16 * ks); acc1 = __builtin_amdgcn_mfma_f32_32x32x16_bf16(b1, a, acc1, 0, 0, 0); }
;         }
;         __syncthreads();
; #pragma unroll
;         for (int r = 0; r < 16; ++r) { red[(wave * 16 + r) * 64 + lane] = acc0[r]; if (MODE == 3) red[8192 + (wave * 16 + r) * 64 + lane] = acc1[r]; }
;         __syncthreads();
;         float v0[2], v1[2];
; #pragma unroll
;         for (int e = 0; e < 2; ++e) { float s0 = 0.f, s1 = 0.f;
; #pragma unroll
;             for (int w = 0; w < 8; ++w) { s0 += red[(w * 16 + 2 * wave + e) * 64 + lane]; if (MODE == 3) s1 += red[8192 + (w * 16 + 2 * wave + e) * 64 + lane]; }
;             v0[e] = s0; v1[e] = s1; }
;         const int reg = 2 * wave;
;         const int col = 32 * ct + (reg & 3) + 8 * (reg >> 2) + 4 * hh;
;         const size_t row = (size_t)(32 * rt + tl);
;         float o0 = v0[0], o1 = v0[1];
;         if (MODE == 1) { if (col < act_cols) { o0 = gelu_t(o0); o1 = gelu_t(o1); } }
;         if (MODE == 2) { const unsigned y = *(const unsigned*)(Yv + row * ldy + col); o0 = bf_lo(y) * pg8::sigmoid_f(o0 + bias[col]); o1 = bf_hi(y) * pg8::sigmoid_f(o1 + bias[col + 1]); }
;         if (MODE == 3) { o0 = pg8::silu_f(o0) * v1[0]; o1 = pg8::silu_f(o1) * v1[1]; }
.LBB0_1218:
	s_add_i32 s85, s85, s94
	s_cmpk_gt_i32 s85, 0x7f
	s_mov_b64 s[8:9], -1
	s_cbranch_scc1 .LBB0_1217
	s_and_b32 s3, s2, 0xffffffe0
	v_or_b32_e32 v0, s3, v22
	v_mad_i64_i32 v[54:55], s[0:1], v0, s10, v[20:21]
	global_load_dwordx4 v[58:61], v[54:55], off
	s_and_b32 s8, s82, 0x60
	v_or_b32_e32 v16, s8, v22
	v_mad_u64_u32 v[56:57], s[0:1], v16, s10, v[18:19]
	s_add_i32 s84, s84, 1
	s_add_i32 s2, s2, s46
	s_add_i32 s82, s82, s71
	v_lshlrev_b32_e32 v16, 11, v16
	s_cmp_gt_u32 s84, 2
	s_cselect_b64 s[8:9], -1, 0
	global_load_dwordx4 v[62:65], v[56:57], off
	global_load_dwordx4 v[66:69], v[54:55], off offset:32
	global_load_dwordx4 v[70:73], v[56:57], off offset:32
	global_load_dwordx4 v[74:77], v[54:55], off offset:64
	global_load_dwordx4 v[78:81], v[56:57], off offset:64
	global_load_dwordx4 v[82:85], v[54:55], off offset:96
	global_load_dwordx4 v[86:89], v[56:57], off offset:96
	global_load_dwordx4 v[90:93], v[54:55], off offset:128
	global_load_dwordx4 v[94:97], v[56:57], off offset:128
	global_load_dwordx4 v[98:101], v[54:55], off offset:160
	global_load_dwordx4 v[102:105], v[56:57], off offset:160
	global_load_dwordx4 v[106:109], v[54:55], off offset:192
	global_load_dwordx4 v[110:113], v[56:57], off offset:192
	global_load_dwordx4 v[114:117], v[54:55], off offset:224
	global_load_dwordx4 v[118:121], v[56:57], off offset:224
	global_load_dwordx4 v[122:125], v[54:55], off offset:256
	global_load_dwordx4 v[126:129], v[56:57], off offset:256
	global_load_dwordx4 v[130:133], v[54:55], off offset:288
	global_load_dwordx4 v[134:137], v[56:57], off offset:288
	global_load_dwordx4 v[138:141], v[54:55], off offset:320
	global_load_dwordx4 v[142:145], v[56:57], off offset:320
	global_load_dwordx4 v[146:149], v[54:55], off offset:352
	global_load_dwordx4 v[150:153], v[56:57], off offset:352
	global_load_dwordx4 v[154:157], v[54:55], off offset:384
	global_load_dwordx4 v[158:161], v[56:57], off offset:384
	global_load_dwordx4 v[162:165], v[54:55], off offset:416
	global_load_dwordx4 v[166:169], v[56:57], off offset:416
	global_load_dwordx4 v[170:173], v[54:55], off offset:448
	global_load_dwordx4 v[174:177], v[56:57], off offset:448
	global_load_dwordx4 v[178:181], v[54:55], off offset:480
	global_load_dwordx4 v[192:195], v[56:57], off offset:480
	global_load_dwordx4 v[196:199], v[54:55], off offset:512
	global_load_dwordx4 v[200:203], v[56:57], off offset:512
	global_load_dwordx4 v[204:207], v[54:55], off offset:544
	global_load_dwordx4 v[208:211], v[56:57], off offset:544
	global_load_dwordx4 v[212:215], v[54:55], off offset:576
	global_load_dwordx4 v[216:219], v[56:57], off offset:576
	global_load_dwordx4 v[220:223], v[54:55], off offset:608
	global_load_dwordx4 v[224:227], v[56:57], off offset:608
	global_load_dwordx4 v[228:231], v[54:55], off offset:640
	global_load_dwordx4 v[234:237], v[56:57], off offset:640
	global_load_dwordx4 v[238:241], v[54:55], off offset:672
	global_load_dwordx4 v[242:245], v[56:57], off offset:672
	s_waitcnt vmcnt(42)
	v_mfma_f32_32x32x16_bf16 v[0:15], v[58:61], v[62:65], 0
	s_waitcnt vmcnt(40)
	v_mfma_f32_32x32x16_bf16 v[0:15], v[66:69], v[70:73], v[0:15]
	s_waitcnt vmcnt(38)
	v_mfma_f32_32x32x16_bf16 v[0:15], v[74:77], v[78:81], v[0:15]
	s_waitcnt vmcnt(36)
	v_mfma_f32_32x32x16_bf16 v[0:15], v[82:85], v[86:89], v[0:15]
	s_waitcnt vmcnt(34)
	v_mfma_f32_32x32x16_bf16 v[0:15], v[90:93], v[94:97], v[0:15]
	s_waitcnt vmcnt(32)
	v_mfma_f32_32x32x16_bf16 v[0:15], v[98:101], v[102:105], v[0:15]
	s_waitcnt vmcnt(30)
	v_mfma_f32_32x32x16_bf16 v[0:15], v[106:109], v[110:113], v[0:15]
	s_waitcnt vmcnt(28)
	v_mfma_f32_32x32x16_bf16 v[0:15], v[114:117], v[118:121], v[0:15]
	s_waitcnt vmcnt(26)
	v_mfma_f32_32x32x16_bf16 v[0:15], v[122:125], v[126:129], v[0:15]
	s_waitcnt vmcnt(24)
	v_mfma_f32_32x32x16_bf16 v[0:15], v[130:133], v[134:137], v[0:15]
	s_waitcnt vmcnt(22)
	v_mfma_f32_32x32x16_bf16 v[0:15], v[138:141], v[142:145], v[0:15]
	s_waitcnt vmcnt(20)
	v_mfma_f32_32x32x16_bf16 v[0:15], v[146:149], v[150:153], v[0:15]
	s_waitcnt vmcnt(18)
	v_mfma_f32_32x32x16_bf16 v[0:15], v[154:157], v[158:161], v[0:15]
	s_waitcnt vmcnt(16)
	v_mfma_f32_32x32x16_bf16 v[0:15], v[162:165], v[166:169], v[0:15]
	s_waitcnt vmcnt(14)
	v_mfma_f32_32x32x16_bf16 v[0:15], v[170:173], v[174:177], v[0:15]
	s_waitcnt vmcnt(12)
	v_mfma_f32_32x32x16_bf16 v[0:15], v[178:181], v[192:195], v[0:15]
	s_waitcnt vmcnt(10)
	v_mfma_f32_32x32x16_bf16 v[0:15], v[196:199], v[200:203], v[0:15]
	s_waitcnt vmcnt(8)
	v_mfma_f32_32x32x16_bf16 v[0:15], v[204:207], v[208:211], v[0:15]
	s_waitcnt vmcnt(6)
	v_mfma_f32_32x32x16_bf16 v[0:15], v[212:215], v[216:219], v[0:15]
	s_waitcnt vmcnt(4)
	v_mfma_f32_32x32x16_bf16 v[0:15], v[220:223], v[224:227], v[0:15]
	s_waitcnt vmcnt(2)
	v_mfma_f32_32x32x16_bf16 v[0:15], v[228:231], v[234:237], v[0:15]
	s_waitcnt vmcnt(0)
	v_mfma_f32_32x32x16_bf16 v[0:15], v[238:241], v[242:245], v[0:15]
	s_barrier
	v_add_u32_e32 v26, s3, v23
	v_ashrrev_i32_e32 v27, 31, v26
	v_lshl_add_u64 v[28:29], s[4:5], 0, v[16:17]
	v_lshl_add_u64 v[26:27], v[26:27], 1, v[28:29]
	s_nop 11
	ds_write2st64_b32 v24, v0, v1 offset1:1
	ds_write2st64_b32 v24, v2, v3 offset0:2 offset1:3
	ds_write2st64_b32 v24, v4, v5 offset0:4 offset1:5
	ds_write2st64_b32 v24, v6, v7 offset0:6 offset1:7
	ds_write2st64_b32 v24, v8, v9 offset0:8 offset1:9
	ds_write2st64_b32 v24, v10, v11 offset0:10 offset1:11
	ds_write2st64_b32 v24, v12, v13 offset0:12 offset1:13
	ds_write2st64_b32 v24, v14, v15 offset0:14 offset1:15
	s_waitcnt lgkmcnt(0)
	s_barrier
	ds_read2st64_b32 v[0:1], v25 offset1:1
	ds_read2st64_b32 v[2:3], v25 offset0:16 offset1:17
	ds_read2st64_b32 v[4:5], v25 offset0:32 offset1:33
	ds_read2st64_b32 v[6:7], v25 offset0:48 offset1:49
	ds_read2st64_b32 v[8:9], v25 offset0:64 offset1:65
	ds_read2st64_b32 v[10:11], v25 offset0:80 offset1:81
	ds_read2st64_b32 v[12:13], v25 offset0:96 offset1:97
	ds_read2st64_b32 v[14:15], v25 offset0:112 offset1:113
	s_waitcnt lgkmcnt(7)
	v_add_f32_e32 v0, 0, v0
	v_add_f32_e32 v1, 0, v1
	s_waitcnt lgkmcnt(6)
	v_add_f32_e32 v0, v0, v2
	v_add_f32_e32 v1, v1, v3
	s_waitcnt lgkmcnt(5)
	v_add_f32_e32 v0, v0, v4
	v_add_f32_e32 v1, v1, v5
	s_waitcnt lgkmcnt(4)
	v_add_f32_e32 v0, v0, v6
	v_add_f32_e32 v1, v1, v7
	s_waitcnt lgkmcnt(3)
	v_add_f32_e32 v0, v0, v8
	v_add_f32_e32 v1, v1, v9
	s_waitcnt lgkmcnt(2)
	v_add_f32_e32 v0, v0, v10
	v_add_f32_e32 v1, v1, v11
	s_waitcnt lgkmcnt(1)
	v_add_f32_e32 v0, v0, v12
	v_add_f32_e32 v1, v1, v13
	s_waitcnt lgkmcnt(0)
	v_add_f32_e32 v0, v0, v14
	v_add_f32_e32 v1, v1, v15
	v_cvt_pk_bf16_f32 v0, v0, v1
	global_store_dword v[26:27], v0, off
	s_branch .LBB0_1217
